# grid barrier two-level: last arriver of each of the 8 shard counters (returning atomic) arrives on a top counter; all workgroups poll only the top counter
# speedup vs baseline: 1.0030x; 1.0030x over previous
; DI int tid_l() { int t = threadIdx.x; asm volatile("" : "+v"(t)); return t; }
; DI void phase0(const Params& p, char* lds) {
;     ...
;   if (blockIdx.x == 0) { const int t_ = tid_l(); if (t_ < 128) ((unsigned*)(ws + OFF_CNT))[t_] = 0u; if (t_ == 128) ((unsigned*)(ws + OFF_CNT))[256] = 0u; }
.LBB0_44:
	s_or_b64 exec, exec, s[4:5]
	v_subrev_u32_e32 v3, s3, v2
	v_cmp_gt_u32_e32 vcc, 9, v3
	s_and_saveexec_b64 s[4:5], vcc
	s_cbranch_execz .LBB0_46
	v_lshlrev_b32_e32 v1, 8, v3
	v_add_u32_e32 v1, 0x1ee14000, v1
	v_mov_b32_e32 v2, 0
	global_store_dword v1, v2, s[10:11] offset:1024

; #define GAS __attribute__((address_space(1)))
; DI void grid_barrier(unsigned* ctr, const unsigned target) {
;   asm volatile("s_waitcnt vmcnt(0)" ::: "memory");
;   __syncthreads();
;   if (threadIdx.x == 0) {
;     __builtin_amdgcn_fence(__ATOMIC_RELEASE, "agent");
;     asm volatile("s_waitcnt vmcnt(0)" ::: "memory");
;     __hip_atomic_fetch_add((GAS unsigned*)ctr, 1u, __ATOMIC_RELAXED, __HIP_MEMORY_SCOPE_AGENT);
;     while (__hip_atomic_load((GAS unsigned*)ctr, __ATOMIC_RELAXED, __HIP_MEMORY_SCOPE_AGENT) < target) __builtin_amdgcn_s_sleep(1);
;     __builtin_amdgcn_fence(__ATOMIC_ACQUIRE, "agent");
;     asm volatile("s_waitcnt vmcnt(0)" ::: "memory");
;   }
;   __syncthreads();
; }
.LBB0_135:
	v_readlane_b32 s3, v254, 12
	s_add_i32 s2, s3, 1
	s_cmp_ge_i32 s2, s79
	s_cbranch_scc1 .LBB0_156
	s_cmp_lg_u32 s3, s78
	s_mov_b64 s[4:5], -1
	s_cbranch_scc0 .LBB0_144
	s_waitcnt vmcnt(0)
	s_waitcnt vmcnt(63) expcnt(7) lgkmcnt(15)
	s_barrier
	s_mov_b64 s[4:5], exec
	v_readlane_b32 s6, v254, 26
	v_readlane_b32 s7, v254, 27
	s_and_b64 s[6:7], s[4:5], s[6:7]
	s_mov_b64 exec, s[6:7]
	s_cbranch_execz .LBB0_143
	s_mov_b64 s[10:11], exec
	buffer_wbl2 sc1
	s_waitcnt vmcnt(0)
	s_waitcnt vmcnt(0)
	v_mbcnt_lo_u32_b32 v0, s10, 0
	s_add_u32 s8, s14, 0x1ee14400
	v_mbcnt_hi_u32_b32 v0, s11, v0
	s_addc_u32 s9, s15, 0
	v_cmp_eq_u32_e32 vcc, 0, v0
	s_and_saveexec_b64 s[12:13], vcc
	s_cbranch_execz .LBB0_140
	s_bcnt1_i32_b64 s3, s[10:11]
	v_mov_b32_e32 v0, s3
	v_readlane_b32 s100, v254, 0
	s_and_b32 s100, s100, 7
	s_lshl_b32 s100, s100, 8
	s_add_u32 s100, s8, s100
	s_addc_u32 s101, s9, 0
	global_atomic_add v0, v1, v0, s[100:101] sc0
.LBB0_140:
	s_or_b64 exec, exec, s[12:13]
	s_load_dword s6, s[80:81], 0x0
	v_readlane_b32 s3, v254, 12
	s_sub_i32 s3, s3, s78
	s_waitcnt lgkmcnt(0)
	s_mul_i32 s3, s6, s3
	s_waitcnt vmcnt(0)
	v_readfirstlane_b32 s100, v0
	s_lshr_b32 s101, s3, 3
	s_add_i32 s100, s100, 1
	s_cmp_lg_u32 s100, s101
	s_cbranch_scc1 .Lgb_nl_10
	v_mov_b32_e32 v0, 1
	global_atomic_add v1, v0, s[8:9] offset:2048
.Lgb_nl_10:
	s_lshr_b32 s3, s3, 5
	global_load_dword v0, v1, s[8:9] offset:2048 sc1
	s_waitcnt vmcnt(0)
	v_cmp_gt_u32_e32 vcc, s3, v0
	s_cbranch_vccz .LBB0_142
.LBB0_141:
	s_sleep 1
	global_load_dword v0, v1, s[8:9] offset:2048 sc1
	s_waitcnt vmcnt(0)
	v_cmp_gt_u32_e32 vcc, s3, v0
	s_cbranch_vccnz .LBB0_141

; #define GAS __attribute__((address_space(1)))
; DI void grid_barrier(unsigned* ctr, const unsigned target) {
;   asm volatile("s_waitcnt vmcnt(0)" ::: "memory");
;   __syncthreads();
;   if (threadIdx.x == 0) {
;     __builtin_amdgcn_fence(__ATOMIC_RELEASE, "agent");
;     asm volatile("s_waitcnt vmcnt(0)" ::: "memory");
;     __hip_atomic_fetch_add((GAS unsigned*)ctr, 1u, __ATOMIC_RELAXED, __HIP_MEMORY_SCOPE_AGENT);
;     while (__hip_atomic_load((GAS unsigned*)ctr, __ATOMIC_RELAXED, __HIP_MEMORY_SCOPE_AGENT) < target) __builtin_amdgcn_s_sleep(1);
;     __builtin_amdgcn_fence(__ATOMIC_ACQUIRE, "agent");
;     asm volatile("s_waitcnt vmcnt(0)" ::: "memory");
;   }
;   __syncthreads();
; }
.LBB0_168:
	v_readlane_b32 s3, v254, 12
	s_add_i32 s14, s3, 2
	s_cmp_ge_i32 s14, s79
	s_cbranch_scc1 .LBB0_189
	s_cmp_lg_u32 s2, s78
	s_mov_b64 s[4:5], -1
	s_cbranch_scc0 .LBB0_177
	s_waitcnt vmcnt(0)
	s_waitcnt vmcnt(63) expcnt(7) lgkmcnt(15)
	s_barrier
	s_mov_b64 s[4:5], exec
	v_readlane_b32 s6, v254, 26
	v_readlane_b32 s7, v254, 27
	s_and_b64 s[6:7], s[4:5], s[6:7]
	s_mov_b64 exec, s[6:7]
	s_cbranch_execz .LBB0_176
	s_mov_b64 s[10:11], exec
	buffer_wbl2 sc1
	s_waitcnt vmcnt(0)
	s_waitcnt vmcnt(0)
	v_mbcnt_lo_u32_b32 v0, s10, 0
	s_add_u32 s8, s26, 0x1ee14400
	v_mbcnt_hi_u32_b32 v0, s11, v0
	s_addc_u32 s9, s27, 0
	v_cmp_eq_u32_e32 vcc, 0, v0
	s_and_saveexec_b64 s[12:13], vcc
	s_cbranch_execz .LBB0_173
	s_bcnt1_i32_b64 s3, s[10:11]
	v_mov_b32_e32 v0, s3
	v_readlane_b32 s100, v254, 0
	s_and_b32 s100, s100, 7
	s_lshl_b32 s100, s100, 8
	s_add_u32 s100, s8, s100
	s_addc_u32 s101, s9, 0
	global_atomic_add v0, v1, v0, s[100:101] sc0
.LBB0_173:
	s_or_b64 exec, exec, s[12:13]
	s_load_dword s3, s[80:81], 0x0
	s_sub_i32 s2, s2, s78
	s_waitcnt lgkmcnt(0)
	s_mul_i32 s2, s3, s2
	s_waitcnt vmcnt(0)
	v_readfirstlane_b32 s100, v0
	s_lshr_b32 s101, s2, 3
	s_add_i32 s100, s100, 1
	s_cmp_lg_u32 s100, s101
	s_cbranch_scc1 .Lgb_nl_9
	v_mov_b32_e32 v0, 1
	global_atomic_add v1, v0, s[8:9] offset:2048
.Lgb_nl_9:
	s_lshr_b32 s2, s2, 5
	global_load_dword v0, v1, s[8:9] offset:2048 sc1
	s_waitcnt vmcnt(0)
	v_cmp_gt_u32_e32 vcc, s2, v0
	s_cbranch_vccz .LBB0_175
.LBB0_174:
	s_sleep 1
	global_load_dword v0, v1, s[8:9] offset:2048 sc1
	s_waitcnt vmcnt(0)
	v_cmp_gt_u32_e32 vcc, s2, v0
	s_cbranch_vccnz .LBB0_174

; #define GAS __attribute__((address_space(1)))
; DI void grid_barrier(unsigned* ctr, const unsigned target) {
;   asm volatile("s_waitcnt vmcnt(0)" ::: "memory");
;   __syncthreads();
;   if (threadIdx.x == 0) {
;     __builtin_amdgcn_fence(__ATOMIC_RELEASE, "agent");
;     asm volatile("s_waitcnt vmcnt(0)" ::: "memory");
;     __hip_atomic_fetch_add((GAS unsigned*)ctr, 1u, __ATOMIC_RELAXED, __HIP_MEMORY_SCOPE_AGENT);
;     while (__hip_atomic_load((GAS unsigned*)ctr, __ATOMIC_RELAXED, __HIP_MEMORY_SCOPE_AGENT) < target) __builtin_amdgcn_s_sleep(1);
;     __builtin_amdgcn_fence(__ATOMIC_ACQUIRE, "agent");
;     asm volatile("s_waitcnt vmcnt(0)" ::: "memory");
;   }
;   __syncthreads();
; }
.LBB0_241:
	v_readlane_b32 s2, v254, 12
	v_readlane_b32 s78, v254, 32
	s_add_i32 s28, s2, 3
	v_readlane_b32 s79, v254, 33
	s_cmp_ge_i32 s28, s79
	s_cbranch_scc1 .LBB0_262
	v_readlane_b32 s6, v254, 50
	v_readlane_b32 s80, v254, 34
	s_cmp_lg_u32 s6, s78
	s_mov_b64 s[4:5], -1
	v_readlane_b32 s81, v254, 35
	s_cbranch_scc0 .LBB0_250
	s_waitcnt vmcnt(0)
	s_barrier
	s_mov_b64 s[4:5], exec
	v_readlane_b32 s2, v254, 26
	v_readlane_b32 s3, v254, 27
	s_and_b64 s[2:3], s[4:5], s[2:3]
	s_mov_b64 exec, s[2:3]
	s_cbranch_execz .LBB0_249
	s_mov_b64 s[10:11], exec
	v_readlane_b32 s2, v254, 48
	buffer_wbl2 sc1
	s_waitcnt vmcnt(0)
	s_waitcnt vmcnt(0)
	v_mbcnt_lo_u32_b32 v0, s10, 0
	v_readlane_b32 s3, v254, 49
	s_add_u32 s8, s2, 0x1ee14400
	v_mbcnt_hi_u32_b32 v0, s11, v0
	s_addc_u32 s9, s3, 0
	v_cmp_eq_u32_e32 vcc, 0, v0
	s_and_saveexec_b64 s[12:13], vcc
	s_cbranch_execz .LBB0_246
	s_bcnt1_i32_b64 s2, s[10:11]
	v_mov_b32_e32 v0, s2
	v_readlane_b32 s100, v254, 0
	s_and_b32 s100, s100, 7
	s_lshl_b32 s100, s100, 8
	s_add_u32 s100, s8, s100
	s_addc_u32 s101, s9, 0
	global_atomic_add v0, v1, v0, s[100:101] sc0
.LBB0_246:
	s_or_b64 exec, exec, s[12:13]
	s_load_dword s3, s[80:81], 0x0
	s_sub_i32 s2, s6, s78
	s_waitcnt lgkmcnt(0)
	s_mul_i32 s2, s3, s2
	s_waitcnt vmcnt(0)
	v_readfirstlane_b32 s100, v0
	s_lshr_b32 s101, s2, 3
	s_add_i32 s100, s100, 1
	s_cmp_lg_u32 s100, s101
	s_cbranch_scc1 .Lgb_nl_8
	v_mov_b32_e32 v0, 1
	global_atomic_add v1, v0, s[8:9] offset:2048

; #define GAS __attribute__((address_space(1)))
; DI void grid_barrier(unsigned* ctr, const unsigned target) {
;   asm volatile("s_waitcnt vmcnt(0)" ::: "memory");
;   __syncthreads();
;   if (threadIdx.x == 0) {
;     __builtin_amdgcn_fence(__ATOMIC_RELEASE, "agent");
;     asm volatile("s_waitcnt vmcnt(0)" ::: "memory");
;     __hip_atomic_fetch_add((GAS unsigned*)ctr, 1u, __ATOMIC_RELAXED, __HIP_MEMORY_SCOPE_AGENT);
;     while (__hip_atomic_load((GAS unsigned*)ctr, __ATOMIC_RELAXED, __HIP_MEMORY_SCOPE_AGENT) < target) __builtin_amdgcn_s_sleep(1);
;     __builtin_amdgcn_fence(__ATOMIC_ACQUIRE, "agent");
;     asm volatile("s_waitcnt vmcnt(0)" ::: "memory");
;   }
;   __syncthreads();
; }
.LBB0_279:
	v_readlane_b32 s2, v254, 12
	s_add_i32 s24, s2, 4
	s_cmp_ge_i32 s24, s79
	s_cbranch_scc1 .LBB0_300
	s_cmp_lg_u32 s28, s78
	s_mov_b64 s[4:5], -1
	s_cbranch_scc0 .LBB0_288
	s_waitcnt vmcnt(0)
	s_barrier
	s_mov_b64 s[4:5], exec
	v_readlane_b32 s2, v254, 26
	v_readlane_b32 s3, v254, 27
	s_and_b64 s[2:3], s[4:5], s[2:3]
	s_mov_b64 exec, s[2:3]
	s_cbranch_execz .LBB0_287
	s_add_u32 s8, s10, 0x1ee14400
	s_addc_u32 s9, s11, 0
	s_mov_b64 s[10:11], exec
	buffer_wbl2 sc1
	s_waitcnt vmcnt(0)
	s_waitcnt vmcnt(0)
	v_mbcnt_lo_u32_b32 v0, s10, 0
	v_mbcnt_hi_u32_b32 v0, s11, v0
	v_cmp_eq_u32_e32 vcc, 0, v0
	s_and_saveexec_b64 s[12:13], vcc
	s_cbranch_execz .LBB0_284
	s_bcnt1_i32_b64 s2, s[10:11]
	v_mov_b32_e32 v0, s2
	v_readlane_b32 s100, v254, 0
	s_and_b32 s100, s100, 7
	s_lshl_b32 s100, s100, 8
	s_add_u32 s100, s8, s100
	s_addc_u32 s101, s9, 0
	global_atomic_add v0, v1, v0, s[100:101] sc0
.LBB0_284:
	s_or_b64 exec, exec, s[12:13]
	s_load_dword s3, s[80:81], 0x0
	s_sub_i32 s2, s28, s78
	s_waitcnt lgkmcnt(0)
	s_mul_i32 s2, s3, s2
	s_waitcnt vmcnt(0)
	v_readfirstlane_b32 s100, v0
	s_lshr_b32 s101, s2, 3
	s_add_i32 s100, s100, 1
	s_cmp_lg_u32 s100, s101
	s_cbranch_scc1 .Lgb_nl_7
	v_mov_b32_e32 v0, 1
	global_atomic_add v1, v0, s[8:9] offset:2048

; #define GAS __attribute__((address_space(1)))
; DI void grid_barrier(unsigned* ctr, const unsigned target) {
;   asm volatile("s_waitcnt vmcnt(0)" ::: "memory");
;   __syncthreads();
;   if (threadIdx.x == 0) {
;     __builtin_amdgcn_fence(__ATOMIC_RELEASE, "agent");
;     asm volatile("s_waitcnt vmcnt(0)" ::: "memory");
;     __hip_atomic_fetch_add((GAS unsigned*)ctr, 1u, __ATOMIC_RELAXED, __HIP_MEMORY_SCOPE_AGENT);
;     while (__hip_atomic_load((GAS unsigned*)ctr, __ATOMIC_RELAXED, __HIP_MEMORY_SCOPE_AGENT) < target) __builtin_amdgcn_s_sleep(1);
;     __builtin_amdgcn_fence(__ATOMIC_ACQUIRE, "agent");
;     asm volatile("s_waitcnt vmcnt(0)" ::: "memory");
;   }
;   __syncthreads();
; }
.LBB0_504:
	v_readlane_b32 s2, v254, 12
	s_add_i32 s3, s2, 1
	s_cmp_ge_i32 s3, s79
	s_cbranch_scc1 .LBB0_525
	s_cmp_lg_u32 s2, s78
	s_mov_b64 s[4:5], -1
	s_cbranch_scc0 .LBB0_513
	s_waitcnt vmcnt(0)
	s_waitcnt vmcnt(63) expcnt(7) lgkmcnt(15)
	s_barrier
	s_mov_b64 s[4:5], exec
	v_readlane_b32 s6, v254, 26
	v_readlane_b32 s7, v254, 27
	s_and_b64 s[6:7], s[4:5], s[6:7]
	s_mov_b64 exec, s[6:7]
	s_cbranch_execz .LBB0_512
	s_load_dword s2, s[80:81], 0x0
	s_mov_b64 s[8:9], exec
	buffer_wbl2 sc1
	s_waitcnt vmcnt(0) lgkmcnt(0)
	s_waitcnt vmcnt(0)
	v_mbcnt_lo_u32_b32 v0, s8, 0
	s_add_u32 s6, s18, 0x1ee14400
	v_mbcnt_hi_u32_b32 v0, s9, v0
	s_addc_u32 s7, s19, 0
	v_cmp_eq_u32_e32 vcc, 0, v0
	s_and_saveexec_b64 s[10:11], vcc
	s_cbranch_execz .LBB0_509
	s_bcnt1_i32_b64 s8, s[8:9]
	v_mov_b32_e32 v0, s8
	v_readlane_b32 s100, v254, 0
	s_and_b32 s100, s100, 7
	s_lshl_b32 s100, s100, 8
	s_add_u32 s100, s6, s100
	s_addc_u32 s101, s7, 0
	global_atomic_add v0, v1, v0, s[100:101] sc0
.LBB0_509:
	s_or_b64 exec, exec, s[10:11]
	v_readlane_b32 s8, v254, 12
	s_sub_i32 s8, s8, s78
	s_mul_i32 s2, s2, s8
	s_waitcnt vmcnt(0)
	v_readfirstlane_b32 s100, v0
	s_lshr_b32 s101, s2, 3
	s_add_i32 s100, s100, 1
	s_cmp_lg_u32 s100, s101
	s_cbranch_scc1 .Lgb_nl_6
	v_mov_b32_e32 v0, 1
	global_atomic_add v1, v0, s[6:7] offset:2048
.Lgb_nl_6:
	s_lshr_b32 s2, s2, 5
	global_load_dword v0, v1, s[6:7] offset:2048 sc1
	s_waitcnt vmcnt(0)
	v_cmp_gt_u32_e32 vcc, s2, v0
	s_cbranch_vccz .LBB0_511
.LBB0_510:
	s_sleep 1
	global_load_dword v0, v1, s[6:7] offset:2048 sc1
	s_waitcnt vmcnt(0)
	v_cmp_gt_u32_e32 vcc, s2, v0
	s_cbranch_vccnz .LBB0_510

; #define GAS __attribute__((address_space(1)))
; DI void grid_barrier(unsigned* ctr, const unsigned target) {
;   asm volatile("s_waitcnt vmcnt(0)" ::: "memory");
;   __syncthreads();
;   if (threadIdx.x == 0) {
;     __builtin_amdgcn_fence(__ATOMIC_RELEASE, "agent");
;     asm volatile("s_waitcnt vmcnt(0)" ::: "memory");
;     __hip_atomic_fetch_add((GAS unsigned*)ctr, 1u, __ATOMIC_RELAXED, __HIP_MEMORY_SCOPE_AGENT);
;     while (__hip_atomic_load((GAS unsigned*)ctr, __ATOMIC_RELAXED, __HIP_MEMORY_SCOPE_AGENT) < target) __builtin_amdgcn_s_sleep(1);
;     __builtin_amdgcn_fence(__ATOMIC_ACQUIRE, "agent");
;     asm volatile("s_waitcnt vmcnt(0)" ::: "memory");
;   }
;   __syncthreads();
; }
.LBB0_537:
	v_readlane_b32 s2, v254, 12
	s_add_i32 s2, s2, 2
	s_cmp_ge_i32 s2, s79
	s_cbranch_scc1 .LBB0_558
	s_cmp_lg_u32 s3, s78
	s_mov_b64 s[8:9], -1
	s_cbranch_scc0 .LBB0_546
	s_waitcnt vmcnt(0)
	s_waitcnt vmcnt(63) expcnt(7) lgkmcnt(15)
	s_barrier
	s_mov_b64 s[8:9], exec
	v_readlane_b32 s10, v254, 26
	v_readlane_b32 s11, v254, 27
	s_and_b64 s[10:11], s[8:9], s[10:11]
	s_mov_b64 exec, s[10:11]
	s_cbranch_execz .LBB0_545
	s_mov_b64 s[10:11], exec
	buffer_wbl2 sc1
	s_waitcnt vmcnt(0)
	s_waitcnt vmcnt(0)
	v_mbcnt_lo_u32_b32 v0, s10, 0
	s_add_u32 s4, s4, 0x1ee14400
	v_mbcnt_hi_u32_b32 v0, s11, v0
	s_addc_u32 s5, s5, 0
	v_cmp_eq_u32_e32 vcc, 0, v0
	s_and_saveexec_b64 s[12:13], vcc
	s_cbranch_execz .LBB0_542
	s_bcnt1_i32_b64 s10, s[10:11]
	v_mov_b32_e32 v0, s10
	v_readlane_b32 s100, v254, 0
	s_and_b32 s100, s100, 7
	s_lshl_b32 s100, s100, 8
	s_add_u32 s100, s4, s100
	s_addc_u32 s101, s5, 0
	global_atomic_add v0, v1, v0, s[100:101] sc0
.LBB0_542:
	s_or_b64 exec, exec, s[12:13]
	s_load_dword s10, s[80:81], 0x0
	s_sub_i32 s3, s3, s78
	s_waitcnt lgkmcnt(0)
	s_mul_i32 s3, s10, s3
	s_waitcnt vmcnt(0)
	v_readfirstlane_b32 s100, v0
	s_lshr_b32 s101, s3, 3
	s_add_i32 s100, s100, 1
	s_cmp_lg_u32 s100, s101
	s_cbranch_scc1 .Lgb_nl_5
	v_mov_b32_e32 v0, 1
	global_atomic_add v1, v0, s[4:5] offset:2048
.Lgb_nl_5:
	s_lshr_b32 s3, s3, 5
	global_load_dword v0, v1, s[4:5] offset:2048 sc1
	s_waitcnt vmcnt(0)
	v_cmp_gt_u32_e32 vcc, s3, v0
	s_cbranch_vccz .LBB0_544
.LBB0_543:
	s_sleep 1
	global_load_dword v0, v1, s[4:5] offset:2048 sc1
	s_waitcnt vmcnt(0)
	v_cmp_gt_u32_e32 vcc, s3, v0
	s_cbranch_vccnz .LBB0_543

; #define GAS __attribute__((address_space(1)))
; DI void grid_barrier(unsigned* ctr, const unsigned target) {
;   asm volatile("s_waitcnt vmcnt(0)" ::: "memory");
;   __syncthreads();
;   if (threadIdx.x == 0) {
;     __builtin_amdgcn_fence(__ATOMIC_RELEASE, "agent");
;     asm volatile("s_waitcnt vmcnt(0)" ::: "memory");
;     __hip_atomic_fetch_add((GAS unsigned*)ctr, 1u, __ATOMIC_RELAXED, __HIP_MEMORY_SCOPE_AGENT);
;     while (__hip_atomic_load((GAS unsigned*)ctr, __ATOMIC_RELAXED, __HIP_MEMORY_SCOPE_AGENT) < target) __builtin_amdgcn_s_sleep(1);
;     __builtin_amdgcn_fence(__ATOMIC_ACQUIRE, "agent");
;     asm volatile("s_waitcnt vmcnt(0)" ::: "memory");
;   }
;   __syncthreads();
; }
.LBB0_564:
	s_or_b64 exec, exec, s[8:9]
	v_readlane_b32 s3, v254, 12
	s_add_i32 s16, s3, 3
	s_cmp_ge_i32 s16, s79
	s_cbranch_scc1 .LBB0_585
	s_cmp_lg_u32 s2, s78
	s_mov_b64 s[8:9], -1
	s_cbranch_scc0 .LBB0_573
	s_waitcnt vmcnt(0)
	s_waitcnt vmcnt(63) expcnt(7) lgkmcnt(15)
	s_barrier
	s_mov_b64 s[8:9], exec
	v_readlane_b32 s10, v254, 26
	v_readlane_b32 s11, v254, 27
	s_and_b64 s[10:11], s[8:9], s[10:11]
	s_mov_b64 exec, s[10:11]
	s_cbranch_execz .LBB0_572
	s_mov_b64 s[10:11], exec
	buffer_wbl2 sc1
	s_waitcnt vmcnt(0)
	s_waitcnt vmcnt(0)
	v_mbcnt_lo_u32_b32 v0, s10, 0
	s_add_u32 s4, s4, 0x1ee14400
	v_mbcnt_hi_u32_b32 v0, s11, v0
	s_addc_u32 s5, s5, 0
	v_cmp_eq_u32_e32 vcc, 0, v0
	s_and_saveexec_b64 s[12:13], vcc
	s_cbranch_execz .LBB0_569
	s_bcnt1_i32_b64 s3, s[10:11]
	v_mov_b32_e32 v0, s3
	v_readlane_b32 s100, v254, 0
	s_and_b32 s100, s100, 7
	s_lshl_b32 s100, s100, 8
	s_add_u32 s100, s4, s100
	s_addc_u32 s101, s5, 0
	global_atomic_add v0, v1, v0, s[100:101] sc0
.LBB0_569:
	s_or_b64 exec, exec, s[12:13]
	s_load_dword s3, s[80:81], 0x0
	s_sub_i32 s2, s2, s78
	s_waitcnt lgkmcnt(0)
	s_mul_i32 s2, s3, s2
	s_waitcnt vmcnt(0)
	v_readfirstlane_b32 s100, v0
	s_lshr_b32 s101, s2, 3
	s_add_i32 s100, s100, 1
	s_cmp_lg_u32 s100, s101
	s_cbranch_scc1 .Lgb_nl_4
	v_mov_b32_e32 v0, 1
	global_atomic_add v1, v0, s[4:5] offset:2048
.Lgb_nl_4:
	s_lshr_b32 s2, s2, 5
	global_load_dword v0, v1, s[4:5] offset:2048 sc1
	s_waitcnt vmcnt(0)
	v_cmp_gt_u32_e32 vcc, s2, v0
	s_cbranch_vccz .LBB0_571
.LBB0_570:
	s_sleep 1
	global_load_dword v0, v1, s[4:5] offset:2048 sc1
	s_waitcnt vmcnt(0)
	v_cmp_gt_u32_e32 vcc, s2, v0
	s_cbranch_vccnz .LBB0_570

; #define GAS __attribute__((address_space(1)))
; DI void grid_barrier(unsigned* ctr, const unsigned target) {
;   asm volatile("s_waitcnt vmcnt(0)" ::: "memory");
;   __syncthreads();
;   if (threadIdx.x == 0) {
;     __builtin_amdgcn_fence(__ATOMIC_RELEASE, "agent");
;     asm volatile("s_waitcnt vmcnt(0)" ::: "memory");
;     __hip_atomic_fetch_add((GAS unsigned*)ctr, 1u, __ATOMIC_RELAXED, __HIP_MEMORY_SCOPE_AGENT);
;     while (__hip_atomic_load((GAS unsigned*)ctr, __ATOMIC_RELAXED, __HIP_MEMORY_SCOPE_AGENT) < target) __builtin_amdgcn_s_sleep(1);
;     __builtin_amdgcn_fence(__ATOMIC_ACQUIRE, "agent");
;     asm volatile("s_waitcnt vmcnt(0)" ::: "memory");
;   }
;   __syncthreads();
; }
.LBB0_672:
	v_readlane_b32 s2, v254, 12
	s_add_i32 s26, s2, 4
	s_cmp_ge_i32 s26, s79
	s_cbranch_scc1 .LBB0_693
	v_readlane_b32 s14, v254, 46
	s_cmp_lg_u32 s14, s78
	s_mov_b64 s[4:5], -1
	s_cbranch_scc0 .LBB0_681
	s_waitcnt vmcnt(0)
	s_barrier
	s_mov_b64 s[4:5], exec
	v_readlane_b32 s2, v254, 26
	v_readlane_b32 s3, v254, 27
	s_and_b64 s[2:3], s[4:5], s[2:3]
	s_mov_b64 exec, s[2:3]
	s_cbranch_execz .LBB0_680
	v_readlane_b32 s2, v254, 44
	s_add_u32 s6, s2, 0x1ee14400
	s_load_dword s2, s[80:81], 0x0
	s_mov_b64 s[8:9], exec
	buffer_wbl2 sc1
	s_waitcnt vmcnt(0) lgkmcnt(0)
	s_waitcnt vmcnt(0)
	v_mbcnt_lo_u32_b32 v0, s8, 0
	v_readlane_b32 s3, v254, 45
	v_mbcnt_hi_u32_b32 v0, s9, v0
	s_addc_u32 s7, s3, 0
	v_cmp_eq_u32_e32 vcc, 0, v0
	s_and_saveexec_b64 s[10:11], vcc
	s_cbranch_execz .LBB0_677
	s_bcnt1_i32_b64 s3, s[8:9]
	v_mov_b32_e32 v0, s3
	v_readlane_b32 s100, v254, 0
	s_and_b32 s100, s100, 7
	s_lshl_b32 s100, s100, 8
	s_add_u32 s100, s6, s100
	s_addc_u32 s101, s7, 0
	global_atomic_add v0, v1, v0, s[100:101] sc0
.LBB0_677:
	s_or_b64 exec, exec, s[10:11]
	s_sub_i32 s3, s14, s78
	s_mul_i32 s2, s2, s3
	s_waitcnt vmcnt(0)
	v_readfirstlane_b32 s100, v0
	s_lshr_b32 s101, s2, 3
	s_add_i32 s100, s100, 1
	s_cmp_lg_u32 s100, s101
	s_cbranch_scc1 .Lgb_nl_3
	v_mov_b32_e32 v0, 1
	global_atomic_add v1, v0, s[6:7] offset:2048

; #define GAS __attribute__((address_space(1)))
; DI void grid_barrier(unsigned* ctr, const unsigned target) {
;   asm volatile("s_waitcnt vmcnt(0)" ::: "memory");
;   __syncthreads();
;   if (threadIdx.x == 0) {
;     __builtin_amdgcn_fence(__ATOMIC_RELEASE, "agent");
;     asm volatile("s_waitcnt vmcnt(0)" ::: "memory");
;     __hip_atomic_fetch_add((GAS unsigned*)ctr, 1u, __ATOMIC_RELAXED, __HIP_MEMORY_SCOPE_AGENT);
;     while (__hip_atomic_load((GAS unsigned*)ctr, __ATOMIC_RELAXED, __HIP_MEMORY_SCOPE_AGENT) < target) __builtin_amdgcn_s_sleep(1);
;     __builtin_amdgcn_fence(__ATOMIC_ACQUIRE, "agent");
;     asm volatile("s_waitcnt vmcnt(0)" ::: "memory");
;   }
;   __syncthreads();
; }
.LBB0_711:
	v_readlane_b32 s2, v254, 12
	s_add_i32 s24, s2, 5
	s_cmp_ge_i32 s24, s79
	v_bfrev_b32_e32 v206, 32
	v_mov_b32_e32 v207, 0xe000000
	s_cbranch_scc1 .LBB0_732
	s_cmp_lg_u32 s26, s78
	s_mov_b64 s[4:5], -1
	s_cbranch_scc0 .LBB0_720
	s_waitcnt vmcnt(0)
	s_barrier
	s_mov_b64 s[4:5], exec
	v_readlane_b32 s2, v254, 26
	v_readlane_b32 s3, v254, 27
	s_and_b64 s[2:3], s[4:5], s[2:3]
	s_mov_b64 exec, s[2:3]
	s_cbranch_execz .LBB0_719
	s_load_dword s2, s[80:81], 0x0
	s_mov_b64 s[8:9], exec
	buffer_wbl2 sc1
	s_waitcnt vmcnt(0) lgkmcnt(0)
	s_waitcnt vmcnt(0)
	v_mbcnt_lo_u32_b32 v0, s8, 0
	s_add_u32 s6, s10, 0x1ee14400
	v_mbcnt_hi_u32_b32 v0, s9, v0
	s_addc_u32 s7, s11, 0
	v_cmp_eq_u32_e32 vcc, 0, v0
	s_and_saveexec_b64 s[10:11], vcc
	s_cbranch_execz .LBB0_716
	s_bcnt1_i32_b64 s3, s[8:9]
	v_mov_b32_e32 v0, s3
	v_readlane_b32 s100, v254, 0
	s_and_b32 s100, s100, 7
	s_lshl_b32 s100, s100, 8
	s_add_u32 s100, s6, s100
	s_addc_u32 s101, s7, 0
	global_atomic_add v0, v1, v0, s[100:101] sc0
.LBB0_716:
	s_or_b64 exec, exec, s[10:11]
	s_sub_i32 s3, s26, s78
	s_mul_i32 s2, s2, s3
	s_waitcnt vmcnt(0)
	v_readfirstlane_b32 s100, v0
	s_lshr_b32 s101, s2, 3
	s_add_i32 s100, s100, 1
	s_cmp_lg_u32 s100, s101
	s_cbranch_scc1 .Lgb_nl_2
	v_mov_b32_e32 v0, 1
	global_atomic_add v1, v0, s[6:7] offset:2048

; DI unsigned pk2(float lo, float hi) { f32x2 v = {lo, hi}; bf16x2v b = __builtin_convertvector(v, bf16x2v); return __builtin_bit_cast(unsigned, b); }
; DI float siluf_(float x) { return x * __builtin_amdgcn_rcpf(1.f + __builtin_amdgcn_exp2f(-LOG2E * x)); }
;   DI void operator()(int tok0, int feat0, f32x16 (&acc)[2][2], int r, int hh) const {
;     const int u0 = (feat0 >> 6) * 32;
; #pragma unroll
;     for (int mt = 0; mt < 2; ++mt) {
;       bf16_t* dst = act + (size_t)(tok0 + mt * 32 + r) * DFF + u0 + 16 * hh;
; #pragma unroll
;       for (int gp = 0; gp < 2; ++gp) {
;         u32x4 o;
; #pragma unroll
;         for (int q = 0; q < 4; ++q) { const int i = 8 * gp + 2 * q; o[q] = pk2(siluf_(acc[0][mt][i]) * acc[1][mt][i], siluf_(acc[0][mt][i + 1]) * acc[1][mt][i + 1]); }
;         *(u32x4*)(dst + 8 * gp) = o;
;       }
;     }
;   }
.Lkexit_4:
	v_mov_b32_e32 v0, v192
	v_mov_b64_e32 v[166:167], s[6:7]
	v_ashrrev_i32_e32 v164, 1, v0
	v_and_b32_e32 v164, 0xffffff80, v164
	v_add_u32_e32 v164, s3, v164
	v_ashrrev_i32_e32 v164, 1, v164
	v_and_b32_e32 v165, 0xdf, v0
	v_or_b32_e32 v187, s8, v165
	v_ashrrev_i32_e32 v165, 31, v164
	v_mad_i64_i32 v[188:189], s[12:13], v187, s69, v[166:167]
	v_lshlrev_b64 v[168:169], 1, v[164:165]
	v_lshl_add_u64 v[164:165], v[188:189], 0, v[168:169]
	v_and_b32_e32 v0, 32, v0
	v_lshl_add_u64 v[164:165], v[164:165], 0, v[0:1]
	v_or_b32_e32 v188, 32, v187
	v_mad_i64_i32 v[188:189], s[12:13], v188, s69, v[166:167]
	v_lshl_add_u64 v[188:189], v[188:189], 0, v[168:169]
	v_lshl_add_u64 v[188:189], v[188:189], 0, v[0:1]
	s_mov_b32 s100, 0xbfb8aa3b
	v_pk_mul_f32 v[238:239], v[114:115], s[100:101] op_sel_hi:[1,0]
	v_pk_mul_f32 v[240:241], v[116:117], s[100:101] op_sel_hi:[1,0]
	v_pk_mul_f32 v[242:243], v[118:119], s[100:101] op_sel_hi:[1,0]
	v_pk_mul_f32 v[244:245], v[120:121], s[100:101] op_sel_hi:[1,0]
	v_exp_f32_e32 v238, v238
	v_exp_f32_e32 v239, v239
	v_exp_f32_e32 v240, v240
	v_exp_f32_e32 v241, v241
	v_exp_f32_e32 v242, v242
	v_exp_f32_e32 v243, v243
	v_exp_f32_e32 v244, v244
	v_exp_f32_e32 v245, v245
	v_pk_add_f32 v[238:239], v[238:239], 1.0 op_sel_hi:[1,0]
	v_pk_add_f32 v[240:241], v[240:241], 1.0 op_sel_hi:[1,0]
	v_pk_add_f32 v[242:243], v[242:243], 1.0 op_sel_hi:[1,0]
	v_pk_add_f32 v[244:245], v[244:245], 1.0 op_sel_hi:[1,0]
	v_rcp_f32_e32 v238, v238
	v_rcp_f32_e32 v239, v239
	v_rcp_f32_e32 v240, v240
	v_rcp_f32_e32 v241, v241
	v_rcp_f32_e32 v242, v242
	v_rcp_f32_e32 v243, v243
	v_rcp_f32_e32 v244, v244
	v_rcp_f32_e32 v245, v245
	v_pk_mul_f32 v[238:239], v[114:115], v[238:239]
	v_pk_mul_f32 v[240:241], v[116:117], v[240:241]
	v_pk_mul_f32 v[242:243], v[118:119], v[242:243]
	v_pk_mul_f32 v[244:245], v[120:121], v[244:245]
	v_pk_mul_f32 v[238:239], v[98:99], v[238:239]
	v_pk_mul_f32 v[240:241], v[100:101], v[240:241]
	v_pk_mul_f32 v[242:243], v[102:103], v[242:243]
	v_pk_mul_f32 v[244:245], v[104:105], v[244:245]
	v_cvt_pk_bf16_f32 v238, v238, v239
	v_cvt_pk_bf16_f32 v239, v240, v241
	v_cvt_pk_bf16_f32 v240, v242, v243
	v_cvt_pk_bf16_f32 v241, v244, v245
	global_store_dwordx4 v[164:165], v[238:241], off
	s_nop 1
	v_pk_mul_f32 v[238:239], v[122:123], s[100:101] op_sel_hi:[1,0]
	v_pk_mul_f32 v[240:241], v[124:125], s[100:101] op_sel_hi:[1,0]
	v_pk_mul_f32 v[242:243], v[126:127], s[100:101] op_sel_hi:[1,0]
	v_pk_mul_f32 v[244:245], v[128:129], s[100:101] op_sel_hi:[1,0]
	v_exp_f32_e32 v238, v238
	v_exp_f32_e32 v239, v239
	v_exp_f32_e32 v240, v240
	v_exp_f32_e32 v241, v241
	v_exp_f32_e32 v242, v242
	v_exp_f32_e32 v243, v243
	v_exp_f32_e32 v244, v244
	v_exp_f32_e32 v245, v245
	v_pk_add_f32 v[238:239], v[238:239], 1.0 op_sel_hi:[1,0]
	v_pk_add_f32 v[240:241], v[240:241], 1.0 op_sel_hi:[1,0]
	v_pk_add_f32 v[242:243], v[242:243], 1.0 op_sel_hi:[1,0]
	v_pk_add_f32 v[244:245], v[244:245], 1.0 op_sel_hi:[1,0]
	v_rcp_f32_e32 v238, v238
	v_rcp_f32_e32 v239, v239
	v_rcp_f32_e32 v240, v240
	v_rcp_f32_e32 v241, v241
	v_rcp_f32_e32 v242, v242
	v_rcp_f32_e32 v243, v243
	v_rcp_f32_e32 v244, v244
	v_rcp_f32_e32 v245, v245
	v_pk_mul_f32 v[238:239], v[122:123], v[238:239]
	v_pk_mul_f32 v[240:241], v[124:125], v[240:241]
	v_pk_mul_f32 v[242:243], v[126:127], v[242:243]
	v_pk_mul_f32 v[244:245], v[128:129], v[244:245]
	v_pk_mul_f32 v[238:239], v[106:107], v[238:239]
	v_pk_mul_f32 v[240:241], v[108:109], v[240:241]
	v_pk_mul_f32 v[242:243], v[110:111], v[242:243]
	v_pk_mul_f32 v[244:245], v[112:113], v[244:245]
	v_cvt_pk_bf16_f32 v238, v238, v239
	v_cvt_pk_bf16_f32 v239, v240, v241
	v_cvt_pk_bf16_f32 v240, v242, v243
	v_cvt_pk_bf16_f32 v241, v244, v245
	global_store_dwordx4 v[164:165], v[238:241], off offset:16
	s_nop 1
	v_pk_mul_f32 v[238:239], v[82:83], s[100:101] op_sel_hi:[1,0]
	v_pk_mul_f32 v[240:241], v[84:85], s[100:101] op_sel_hi:[1,0]
	v_pk_mul_f32 v[242:243], v[86:87], s[100:101] op_sel_hi:[1,0]
	v_pk_mul_f32 v[244:245], v[88:89], s[100:101] op_sel_hi:[1,0]
	v_exp_f32_e32 v238, v238
	v_exp_f32_e32 v239, v239
	v_exp_f32_e32 v240, v240
	v_exp_f32_e32 v241, v241
	v_exp_f32_e32 v242, v242
	v_exp_f32_e32 v243, v243
	v_exp_f32_e32 v244, v244
	v_exp_f32_e32 v245, v245
	v_pk_add_f32 v[238:239], v[238:239], 1.0 op_sel_hi:[1,0]
	v_pk_add_f32 v[240:241], v[240:241], 1.0 op_sel_hi:[1,0]
	v_pk_add_f32 v[242:243], v[242:243], 1.0 op_sel_hi:[1,0]
	v_pk_add_f32 v[244:245], v[244:245], 1.0 op_sel_hi:[1,0]
	v_rcp_f32_e32 v238, v238
	v_rcp_f32_e32 v239, v239
	v_rcp_f32_e32 v240, v240
	v_rcp_f32_e32 v241, v241
	v_rcp_f32_e32 v242, v242
	v_rcp_f32_e32 v243, v243
	v_rcp_f32_e32 v244, v244
	v_rcp_f32_e32 v245, v245
	v_pk_mul_f32 v[238:239], v[82:83], v[238:239]
	v_pk_mul_f32 v[240:241], v[84:85], v[240:241]
	v_pk_mul_f32 v[242:243], v[86:87], v[242:243]
	v_pk_mul_f32 v[244:245], v[88:89], v[244:245]
	v_pk_mul_f32 v[238:239], v[66:67], v[238:239]
	v_pk_mul_f32 v[240:241], v[68:69], v[240:241]
	v_pk_mul_f32 v[242:243], v[70:71], v[242:243]
	v_pk_mul_f32 v[244:245], v[72:73], v[244:245]
	v_cvt_pk_bf16_f32 v238, v238, v239
	v_cvt_pk_bf16_f32 v239, v240, v241
	v_cvt_pk_bf16_f32 v240, v242, v243
	v_cvt_pk_bf16_f32 v241, v244, v245
	global_store_dwordx4 v[188:189], v[238:241], off
	s_nop 1
	v_pk_mul_f32 v[238:239], v[90:91], s[100:101] op_sel_hi:[1,0]
	v_pk_mul_f32 v[240:241], v[92:93], s[100:101] op_sel_hi:[1,0]
	v_pk_mul_f32 v[242:243], v[94:95], s[100:101] op_sel_hi:[1,0]
	v_pk_mul_f32 v[244:245], v[96:97], s[100:101] op_sel_hi:[1,0]
	v_exp_f32_e32 v238, v238
	v_exp_f32_e32 v239, v239
	v_exp_f32_e32 v240, v240
	v_exp_f32_e32 v241, v241
	v_exp_f32_e32 v242, v242
	v_exp_f32_e32 v243, v243
; DI unsigned pk2(float lo, float hi) { f32x2 v = {lo, hi}; bf16x2v b = __builtin_convertvector(v, bf16x2v); return __builtin_bit_cast(unsigned, b); }
; DI float siluf_(float x) { return x * __builtin_amdgcn_rcpf(1.f + __builtin_amdgcn_exp2f(-LOG2E * x)); }
;   DI void operator()(int tok0, int feat0, f32x16 (&acc)[2][2], int r, int hh) const {
;     const int u0 = (feat0 >> 6) * 32;
; #pragma unroll
;     for (int mt = 0; mt < 2; ++mt) {
;       bf16_t* dst = act + (size_t)(tok0 + mt * 32 + r) * DFF + u0 + 16 * hh;
; #pragma unroll
;       for (int gp = 0; gp < 2; ++gp) {
;         u32x4 o;
; #pragma unroll
;         for (int q = 0; q < 4; ++q) { const int i = 8 * gp + 2 * q; o[q] = pk2(siluf_(acc[0][mt][i]) * acc[1][mt][i], siluf_(acc[0][mt][i + 1]) * acc[1][mt][i + 1]); }
;         *(u32x4*)(dst + 8 * gp) = o;
;       }
;     }
;   }
	v_exp_f32_e32 v244, v244
	v_exp_f32_e32 v245, v245
	v_pk_add_f32 v[238:239], v[238:239], 1.0 op_sel_hi:[1,0]
	v_pk_add_f32 v[240:241], v[240:241], 1.0 op_sel_hi:[1,0]
	v_pk_add_f32 v[242:243], v[242:243], 1.0 op_sel_hi:[1,0]
	v_pk_add_f32 v[244:245], v[244:245], 1.0 op_sel_hi:[1,0]
	v_rcp_f32_e32 v238, v238
	v_rcp_f32_e32 v239, v239
	v_rcp_f32_e32 v240, v240
	v_rcp_f32_e32 v241, v241
	v_rcp_f32_e32 v242, v242
	v_rcp_f32_e32 v243, v243
	v_rcp_f32_e32 v244, v244
	v_rcp_f32_e32 v245, v245
	v_pk_mul_f32 v[238:239], v[90:91], v[238:239]
	v_pk_mul_f32 v[240:241], v[92:93], v[240:241]
	v_pk_mul_f32 v[242:243], v[94:95], v[242:243]
	v_pk_mul_f32 v[244:245], v[96:97], v[244:245]
	v_pk_mul_f32 v[238:239], v[74:75], v[238:239]
	v_pk_mul_f32 v[240:241], v[76:77], v[240:241]
	v_pk_mul_f32 v[242:243], v[78:79], v[242:243]
	v_pk_mul_f32 v[244:245], v[80:81], v[244:245]
	v_cvt_pk_bf16_f32 v238, v238, v239
	v_cvt_pk_bf16_f32 v239, v240, v241
	v_cvt_pk_bf16_f32 v240, v242, v243
	v_cvt_pk_bf16_f32 v241, v244, v245
	global_store_dwordx4 v[188:189], v[238:241], off offset:16
	s_nop 1
	v_pk_mul_f32 v[238:239], v[50:51], s[100:101] op_sel_hi:[1,0]
	v_pk_mul_f32 v[240:241], v[52:53], s[100:101] op_sel_hi:[1,0]
	v_pk_mul_f32 v[242:243], v[54:55], s[100:101] op_sel_hi:[1,0]
	v_pk_mul_f32 v[244:245], v[56:57], s[100:101] op_sel_hi:[1,0]
	v_exp_f32_e32 v238, v238
	v_exp_f32_e32 v239, v239
	v_exp_f32_e32 v240, v240
	v_exp_f32_e32 v241, v241
	v_exp_f32_e32 v242, v242
	v_exp_f32_e32 v243, v243
	v_exp_f32_e32 v244, v244
	v_exp_f32_e32 v245, v245
	v_pk_add_f32 v[238:239], v[238:239], 1.0 op_sel_hi:[1,0]
	v_pk_add_f32 v[240:241], v[240:241], 1.0 op_sel_hi:[1,0]
	v_pk_add_f32 v[242:243], v[242:243], 1.0 op_sel_hi:[1,0]
	v_pk_add_f32 v[244:245], v[244:245], 1.0 op_sel_hi:[1,0]
	v_rcp_f32_e32 v238, v238
	v_rcp_f32_e32 v239, v239
	v_rcp_f32_e32 v240, v240
	v_rcp_f32_e32 v241, v241
	v_rcp_f32_e32 v242, v242
	v_rcp_f32_e32 v243, v243
	v_rcp_f32_e32 v244, v244
	v_rcp_f32_e32 v245, v245
	v_pk_mul_f32 v[238:239], v[50:51], v[238:239]
	v_pk_mul_f32 v[240:241], v[52:53], v[240:241]
	v_pk_mul_f32 v[242:243], v[54:55], v[242:243]
	v_pk_mul_f32 v[244:245], v[56:57], v[244:245]
	v_pk_mul_f32 v[238:239], v[34:35], v[238:239]
	v_pk_mul_f32 v[240:241], v[36:37], v[240:241]
	v_pk_mul_f32 v[242:243], v[38:39], v[242:243]
	v_pk_mul_f32 v[244:245], v[40:41], v[244:245]
	v_cvt_pk_bf16_f32 v238, v238, v239
	v_cvt_pk_bf16_f32 v239, v240, v241
	v_cvt_pk_bf16_f32 v240, v242, v243
	v_cvt_pk_bf16_f32 v241, v244, v245
	global_store_dwordx4 v[164:165], v[238:241], off offset:64
	s_nop 1
	v_pk_mul_f32 v[238:239], v[58:59], s[100:101] op_sel_hi:[1,0]
	v_pk_mul_f32 v[240:241], v[60:61], s[100:101] op_sel_hi:[1,0]
	v_pk_mul_f32 v[242:243], v[62:63], s[100:101] op_sel_hi:[1,0]
	v_pk_mul_f32 v[244:245], v[64:65], s[100:101] op_sel_hi:[1,0]
	v_exp_f32_e32 v238, v238
	v_exp_f32_e32 v239, v239
	v_exp_f32_e32 v240, v240
	v_exp_f32_e32 v241, v241
	v_exp_f32_e32 v242, v242
	v_exp_f32_e32 v243, v243
	v_exp_f32_e32 v244, v244
	v_exp_f32_e32 v245, v245
	v_pk_add_f32 v[238:239], v[238:239], 1.0 op_sel_hi:[1,0]
	v_pk_add_f32 v[240:241], v[240:241], 1.0 op_sel_hi:[1,0]
	v_pk_add_f32 v[242:243], v[242:243], 1.0 op_sel_hi:[1,0]
	v_pk_add_f32 v[244:245], v[244:245], 1.0 op_sel_hi:[1,0]
	v_rcp_f32_e32 v238, v238
	v_rcp_f32_e32 v239, v239
	v_rcp_f32_e32 v240, v240
	v_rcp_f32_e32 v241, v241
	v_rcp_f32_e32 v242, v242
	v_rcp_f32_e32 v243, v243
	v_rcp_f32_e32 v244, v244
	v_rcp_f32_e32 v245, v245
	v_pk_mul_f32 v[238:239], v[58:59], v[238:239]
	v_pk_mul_f32 v[240:241], v[60:61], v[240:241]
	v_pk_mul_f32 v[242:243], v[62:63], v[242:243]
	v_pk_mul_f32 v[244:245], v[64:65], v[244:245]
	v_pk_mul_f32 v[238:239], v[42:43], v[238:239]
	v_pk_mul_f32 v[240:241], v[44:45], v[240:241]
	v_pk_mul_f32 v[242:243], v[46:47], v[242:243]
	v_pk_mul_f32 v[244:245], v[48:49], v[244:245]
	v_cvt_pk_bf16_f32 v238, v238, v239
	v_cvt_pk_bf16_f32 v239, v240, v241
	v_cvt_pk_bf16_f32 v240, v242, v243
	v_cvt_pk_bf16_f32 v241, v244, v245
	global_store_dwordx4 v[164:165], v[238:241], off offset:80
	s_nop 1
	v_pk_mul_f32 v[238:239], v[18:19], s[100:101] op_sel_hi:[1,0]
	v_pk_mul_f32 v[240:241], v[20:21], s[100:101] op_sel_hi:[1,0]
; #define GAS __attribute__((address_space(1)))
; DI unsigned pk2(float lo, float hi) { f32x2 v = {lo, hi}; bf16x2v b = __builtin_convertvector(v, bf16x2v); return __builtin_bit_cast(unsigned, b); }
; DI float siluf_(float x) { return x * __builtin_amdgcn_rcpf(1.f + __builtin_amdgcn_exp2f(-LOG2E * x)); }
;   DI void operator()(int tok0, int feat0, f32x16 (&acc)[2][2], int r, int hh) const {
;     const int u0 = (feat0 >> 6) * 32;
; #pragma unroll
;     for (int mt = 0; mt < 2; ++mt) {
;       bf16_t* dst = act + (size_t)(tok0 + mt * 32 + r) * DFF + u0 + 16 * hh;
; #pragma unroll
;       for (int gp = 0; gp < 2; ++gp) {
;         u32x4 o;
; #pragma unroll
;         for (int q = 0; q < 4; ++q) { const int i = 8 * gp + 2 * q; o[q] = pk2(siluf_(acc[0][mt][i]) * acc[1][mt][i], siluf_(acc[0][mt][i + 1]) * acc[1][mt][i + 1]); }
;         *(u32x4*)(dst + 8 * gp) = o;
;       }
;     }
;   }
; DI void grid_barrier(unsigned* ctr, const unsigned target) {
;   asm volatile("s_waitcnt vmcnt(0)" ::: "memory");
;   __syncthreads();
;   if (threadIdx.x == 0) {
;     __builtin_amdgcn_fence(__ATOMIC_RELEASE, "agent");
;     asm volatile("s_waitcnt vmcnt(0)" ::: "memory");
;     __hip_atomic_fetch_add((GAS unsigned*)ctr, 1u, __ATOMIC_RELAXED, __HIP_MEMORY_SCOPE_AGENT);
;     while (__hip_atomic_load((GAS unsigned*)ctr, __ATOMIC_RELAXED, __HIP_MEMORY_SCOPE_AGENT) < target) __builtin_amdgcn_s_sleep(1);
;     __builtin_amdgcn_fence(__ATOMIC_ACQUIRE, "agent");
	v_pk_mul_f32 v[242:243], v[22:23], s[100:101] op_sel_hi:[1,0]
	v_pk_mul_f32 v[244:245], v[24:25], s[100:101] op_sel_hi:[1,0]
	v_exp_f32_e32 v238, v238
	v_exp_f32_e32 v239, v239
	v_exp_f32_e32 v240, v240
	v_exp_f32_e32 v241, v241
	v_exp_f32_e32 v242, v242
	v_exp_f32_e32 v243, v243
	v_exp_f32_e32 v244, v244
	v_exp_f32_e32 v245, v245
	v_pk_add_f32 v[238:239], v[238:239], 1.0 op_sel_hi:[1,0]
	v_pk_add_f32 v[240:241], v[240:241], 1.0 op_sel_hi:[1,0]
	v_pk_add_f32 v[242:243], v[242:243], 1.0 op_sel_hi:[1,0]
	v_pk_add_f32 v[244:245], v[244:245], 1.0 op_sel_hi:[1,0]
	v_rcp_f32_e32 v238, v238
	v_rcp_f32_e32 v239, v239
	v_rcp_f32_e32 v240, v240
	v_rcp_f32_e32 v241, v241
	v_rcp_f32_e32 v242, v242
	v_rcp_f32_e32 v243, v243
	v_rcp_f32_e32 v244, v244
	v_rcp_f32_e32 v245, v245
	v_pk_mul_f32 v[238:239], v[18:19], v[238:239]
	v_pk_mul_f32 v[240:241], v[20:21], v[240:241]
	v_pk_mul_f32 v[242:243], v[22:23], v[242:243]
	v_pk_mul_f32 v[244:245], v[24:25], v[244:245]
	v_pk_mul_f32 v[238:239], v[2:3], v[238:239]
	v_pk_mul_f32 v[240:241], v[4:5], v[240:241]
	v_pk_mul_f32 v[242:243], v[6:7], v[242:243]
	v_pk_mul_f32 v[244:245], v[8:9], v[244:245]
	v_cvt_pk_bf16_f32 v238, v238, v239
	v_cvt_pk_bf16_f32 v239, v240, v241
	v_cvt_pk_bf16_f32 v240, v242, v243
	v_cvt_pk_bf16_f32 v241, v244, v245
	global_store_dwordx4 v[188:189], v[238:241], off offset:64
	s_nop 1
	v_pk_mul_f32 v[238:239], v[26:27], s[100:101] op_sel_hi:[1,0]
	v_pk_mul_f32 v[240:241], v[28:29], s[100:101] op_sel_hi:[1,0]
	v_pk_mul_f32 v[242:243], v[30:31], s[100:101] op_sel_hi:[1,0]
	v_pk_mul_f32 v[244:245], v[32:33], s[100:101] op_sel_hi:[1,0]
	v_exp_f32_e32 v238, v238
	v_exp_f32_e32 v239, v239
	v_exp_f32_e32 v240, v240
	v_exp_f32_e32 v241, v241
	v_exp_f32_e32 v242, v242
	v_exp_f32_e32 v243, v243
	v_exp_f32_e32 v244, v244
	v_exp_f32_e32 v245, v245
	v_pk_add_f32 v[238:239], v[238:239], 1.0 op_sel_hi:[1,0]
	v_pk_add_f32 v[240:241], v[240:241], 1.0 op_sel_hi:[1,0]
	v_pk_add_f32 v[242:243], v[242:243], 1.0 op_sel_hi:[1,0]
	v_pk_add_f32 v[244:245], v[244:245], 1.0 op_sel_hi:[1,0]
	v_rcp_f32_e32 v238, v238
	v_rcp_f32_e32 v239, v239
	v_rcp_f32_e32 v240, v240
	v_rcp_f32_e32 v241, v241
	v_rcp_f32_e32 v242, v242
	v_rcp_f32_e32 v243, v243
	v_rcp_f32_e32 v244, v244
	v_rcp_f32_e32 v245, v245
	v_pk_mul_f32 v[238:239], v[26:27], v[238:239]
	v_pk_mul_f32 v[240:241], v[28:29], v[240:241]
	v_pk_mul_f32 v[242:243], v[30:31], v[242:243]
	v_pk_mul_f32 v[244:245], v[32:33], v[244:245]
	v_pk_mul_f32 v[238:239], v[10:11], v[238:239]
	v_pk_mul_f32 v[240:241], v[12:13], v[240:241]
	v_pk_mul_f32 v[242:243], v[14:15], v[242:243]
	v_pk_mul_f32 v[244:245], v[16:17], v[244:245]
	v_cvt_pk_bf16_f32 v238, v238, v239
	v_cvt_pk_bf16_f32 v239, v240, v241
	v_cvt_pk_bf16_f32 v240, v242, v243
	v_cvt_pk_bf16_f32 v241, v244, v245
	global_store_dwordx4 v[188:189], v[238:241], off offset:80
	s_nop 1
	s_and_b64 vcc, exec, s[4:5]
	s_mov_b32 s16, s9
	s_cbranch_vccz .LBB0_736
	s_add_i32 s25, s24, 1
	s_cmp_ge_i32 s25, s79
	s_cbranch_scc1 .LBB0_762
	s_cmp_lg_u32 s24, s78
	s_mov_b64 s[4:5], -1
	v_mov_b32_e32 v206, v198
	v_mov_b32_e32 v207, v199
	s_cbranch_scc0 .LBB0_750
	s_waitcnt vmcnt(0)
	s_barrier
	s_mov_b64 s[4:5], exec
	v_readlane_b32 s2, v254, 26
	v_readlane_b32 s3, v254, 27
	s_and_b64 s[2:3], s[4:5], s[2:3]
	s_mov_b64 exec, s[2:3]
	s_cbranch_execz .LBB0_749
	s_load_dword s2, s[80:81], 0x0
	s_mov_b64 s[8:9], exec
	buffer_wbl2 sc1
	s_waitcnt vmcnt(0) lgkmcnt(0)
	s_waitcnt vmcnt(0)
	v_mbcnt_lo_u32_b32 v0, s8, 0
	s_add_u32 s6, s10, 0x1ee14400
	v_mbcnt_hi_u32_b32 v0, s9, v0
	s_addc_u32 s7, s11, 0
	v_cmp_eq_u32_e32 vcc, 0, v0
	s_and_saveexec_b64 s[10:11], vcc
	s_cbranch_execz .LBB0_746
	s_bcnt1_i32_b64 s3, s[8:9]
	v_mov_b32_e32 v0, s3
	v_readlane_b32 s100, v254, 0
	s_and_b32 s100, s100, 7
	s_lshl_b32 s100, s100, 8
	s_add_u32 s100, s6, s100
	s_addc_u32 s101, s7, 0
	global_atomic_add v0, v1, v0, s[100:101] sc0
.LBB0_746:
	s_or_b64 exec, exec, s[10:11]
	s_sub_i32 s3, s24, s78
	s_mul_i32 s2, s2, s3
	s_waitcnt vmcnt(0)
	v_readfirstlane_b32 s100, v0
	s_lshr_b32 s101, s2, 3
	s_add_i32 s100, s100, 1
	s_cmp_lg_u32 s100, s101
	s_cbranch_scc1 .Lgb_nl_1
	v_mov_b32_e32 v0, 1
	global_atomic_add v1, v0, s[6:7] offset:2048

; #define GAS __attribute__((address_space(1)))
; DI void grid_barrier(unsigned* ctr, const unsigned target) {
;   asm volatile("s_waitcnt vmcnt(0)" ::: "memory");
;   __syncthreads();
;   if (threadIdx.x == 0) {
;     __builtin_amdgcn_fence(__ATOMIC_RELEASE, "agent");
;     asm volatile("s_waitcnt vmcnt(0)" ::: "memory");
;     __hip_atomic_fetch_add((GAS unsigned*)ctr, 1u, __ATOMIC_RELAXED, __HIP_MEMORY_SCOPE_AGENT);
;     while (__hip_atomic_load((GAS unsigned*)ctr, __ATOMIC_RELAXED, __HIP_MEMORY_SCOPE_AGENT) < target) __builtin_amdgcn_s_sleep(1);
;     __builtin_amdgcn_fence(__ATOMIC_ACQUIRE, "agent");
;     asm volatile("s_waitcnt vmcnt(0)" ::: "memory");
;   }
;   __syncthreads();
; }
.LBB0_780:
	s_cmp_lg_u32 s25, s78
	s_mov_b64 s[4:5], -1
	s_cbranch_scc0 .LBB0_788
	s_waitcnt vmcnt(0)
	s_barrier
	s_mov_b64 s[4:5], exec
	v_readlane_b32 s2, v254, 26
	v_readlane_b32 s3, v254, 27
	s_and_b64 s[2:3], s[4:5], s[2:3]
	s_mov_b64 exec, s[2:3]
	s_cbranch_execz .LBB0_787
	s_load_dword s2, s[80:81], 0x0
	s_mov_b64 s[8:9], exec
	buffer_wbl2 sc1
	s_waitcnt vmcnt(0) lgkmcnt(0)
	s_waitcnt vmcnt(0)
	v_mbcnt_lo_u32_b32 v0, s8, 0
	s_add_u32 s6, s14, 0x1ee14400
	v_mbcnt_hi_u32_b32 v0, s9, v0
	s_addc_u32 s7, s15, 0
	v_cmp_eq_u32_e32 vcc, 0, v0
	s_and_saveexec_b64 s[10:11], vcc
	s_cbranch_execz .LBB0_784
	s_bcnt1_i32_b64 s3, s[8:9]
	v_mov_b32_e32 v0, s3
	v_readlane_b32 s100, v254, 0
	s_and_b32 s100, s100, 7
	s_lshl_b32 s100, s100, 8
	s_add_u32 s100, s6, s100
	s_addc_u32 s101, s7, 0
	global_atomic_add v0, v1, v0, s[100:101] sc0
.LBB0_784:
	s_or_b64 exec, exec, s[10:11]
	s_sub_i32 s3, s25, s78
	s_mul_i32 s2, s2, s3
	s_waitcnt vmcnt(0)
	v_readfirstlane_b32 s100, v0
	s_lshr_b32 s101, s2, 3
	s_add_i32 s100, s100, 1
	s_cmp_lg_u32 s100, s101
	s_cbranch_scc1 .Lgb_nl_0
	v_mov_b32_e32 v0, 1
	global_atomic_add v1, v0, s[6:7] offset:2048
